# v079 + next-tile LDS-DMA pieces issued one at a time inside the softmax instead of as a block after the barrier
# baseline (speedup 1.0000x reference)
.LBB0_511:
.LBB0_513:
	s_lshl_b32 s4, s76, 14
	v_add3_u32 v236, s4, v221, v220
	ds_read_b128 v[192:195], v236
	ds_read_b128 v[196:199], v236 offset:8192
	v_add3_u32 v236, s4, v222, v220
	ds_read_b128 v[200:203], v236
	ds_read_b128 v[204:207], v236 offset:8192
	v_add3_u32 v236, s4, v223, v220
	ds_read_b128 v[240:243], v236
	ds_read_b128 v[244:247], v236 offset:8192
	v_add3_u32 v236, s4, v224, v220
	ds_read_b128 v[248:251], v236
	ds_read_b128 v[252:255], v236 offset:8192
	s_waitcnt lgkmcnt(7)
	v_mfma_f32_32x32x16_bf16 v[144:159], v[192:195], v[160:163], 0
	s_waitcnt lgkmcnt(6)
	v_mfma_f32_32x32x16_bf16 v[128:143], v[196:199], v[160:163], 0
	v_add3_u32 v236, s4, v225, v220
	ds_read_b128 v[192:195], v236
	ds_read_b128 v[196:199], v236 offset:8192
	s_waitcnt lgkmcnt(7)
	v_mfma_f32_32x32x16_bf16 v[144:159], v[200:203], v[164:167], v[144:159]
	s_waitcnt lgkmcnt(6)
	v_mfma_f32_32x32x16_bf16 v[128:143], v[204:207], v[164:167], v[128:143]
	v_add3_u32 v236, s4, v227, v220
	ds_read_b128 v[200:203], v236
	ds_read_b128 v[204:207], v236 offset:8192
	s_waitcnt lgkmcnt(7)
	v_mfma_f32_32x32x16_bf16 v[144:159], v[240:243], v[168:171], v[144:159]
	s_waitcnt lgkmcnt(6)
	v_mfma_f32_32x32x16_bf16 v[128:143], v[244:247], v[168:171], v[128:143]
	v_add3_u32 v236, s4, v228, v220
	ds_read_b128 v[240:243], v236
	ds_read_b128 v[244:247], v236 offset:8192
	s_waitcnt lgkmcnt(7)
	v_mfma_f32_32x32x16_bf16 v[144:159], v[248:251], v[172:175], v[144:159]
	s_waitcnt lgkmcnt(6)
	v_mfma_f32_32x32x16_bf16 v[128:143], v[252:255], v[172:175], v[128:143]
	v_add3_u32 v236, s4, v229, v220
	ds_read_b128 v[248:251], v236
	ds_read_b128 v[252:255], v236 offset:8192
	s_waitcnt lgkmcnt(7)
	v_mfma_f32_32x32x16_bf16 v[144:159], v[192:195], v[176:179], v[144:159]
	s_waitcnt lgkmcnt(6)
	v_mfma_f32_32x32x16_bf16 v[128:143], v[196:199], v[176:179], v[128:143]
	s_waitcnt lgkmcnt(5)
	v_mfma_f32_32x32x16_bf16 v[144:159], v[200:203], v[180:183], v[144:159]
	s_waitcnt lgkmcnt(4)
	v_mfma_f32_32x32x16_bf16 v[128:143], v[204:207], v[180:183], v[128:143]
	s_waitcnt lgkmcnt(3)
	v_mfma_f32_32x32x16_bf16 v[144:159], v[240:243], v[184:187], v[144:159]
	s_waitcnt lgkmcnt(2)
	v_mfma_f32_32x32x16_bf16 v[128:143], v[244:247], v[184:187], v[128:143]
	s_waitcnt lgkmcnt(1)
	v_mfma_f32_32x32x16_bf16 v[144:159], v[248:251], v[188:191], v[144:159]
	s_waitcnt lgkmcnt(0)
	v_mfma_f32_32x32x16_bf16 v[128:143], v[252:255], v[188:191], v[128:143]
	s_nop 9
	v_max_f32_e32 v192, v144, v145
	v_max3_f32 v192, v192, v146, v147
	v_max3_f32 v192, v192, v148, v149
	v_max3_f32 v192, v192, v150, v151
	v_max3_f32 v192, v192, v152, v153
	v_max3_f32 v192, v192, v154, v155
	v_max3_f32 v192, v192, v156, v157
	v_max3_f32 v192, v192, v158, v159
	v_max3_f32 v192, v192, v128, v129
	v_max3_f32 v192, v192, v130, v131
	v_max3_f32 v192, v192, v132, v133
	v_max3_f32 v192, v192, v134, v135
	v_max3_f32 v192, v192, v136, v137
	v_max3_f32 v192, v192, v138, v139
	v_max3_f32 v192, v192, v140, v141
	v_max3_f32 v192, v192, v142, v143
	v_mov_b32_e32 v193, v192
	s_nop 1
	v_permlane32_swap_b32_e32 v192, v193
	v_max_f32_e32 v192, v192, v193
	v_sub_f32_e32 v193, v192, v231
	v_cmp_ge_f32_e32 vcc, s38, v193
	v_max_f32_e32 v234, v231, v192
	v_sub_f32_e32 v192, v231, v234
	v_mul_f32_e32 v192, 0x3e0293ee, v192
	v_exp_f32_e32 v192, v192
	s_cmp_eq_u64 vcc, exec
	s_cselect_b64 s[4:5], -1, 0
	v_cndmask_b32_e64 v233, v192, 1.0, s[4:5]
	v_cmp_gt_f32_e32 vcc, 1.0, v233
	s_cbranch_vccz .LBB0_517
	s_and_saveexec_b64 s[24:25], s[0:1]
	ds_write_b32 v226, v233 offset:128
	s_or_b64 exec, exec, s[24:25]
	s_waitcnt lgkmcnt(0)
	v_add_u32_e32 v192, s21, v210
	ds_read_b128 v[204:207], v192 offset:224
	ds_read_b128 v[200:203], v192 offset:192
	ds_read_b128 v[196:199], v192 offset:160
	ds_read_b128 v[192:195], v192 offset:128
	s_waitcnt lgkmcnt(3)
	v_pk_mul_f32 v[12:13], v[12:13], v[204:205]
	s_waitcnt lgkmcnt(2)
	v_pk_mul_f32 v[8:9], v[8:9], v[200:201]
	s_waitcnt lgkmcnt(1)
	v_pk_mul_f32 v[4:5], v[4:5], v[196:197]
	v_pk_mul_f32 v[14:15], v[14:15], v[206:207]
	v_pk_mul_f32 v[10:11], v[10:11], v[202:203]
	v_pk_mul_f32 v[6:7], v[6:7], v[198:199]
	s_waitcnt lgkmcnt(0)
	v_pk_mul_f32 v[2:3], v[2:3], v[194:195]
	v_pk_mul_f32 v[0:1], v[0:1], v[192:193]
	v_pk_mul_f32 v[124:125], v[124:125], v[204:205]
	v_pk_mul_f32 v[120:121], v[120:121], v[200:201]
	v_pk_mul_f32 v[116:117], v[116:117], v[196:197]
	v_pk_mul_f32 v[126:127], v[126:127], v[206:207]
	v_pk_mul_f32 v[122:123], v[122:123], v[202:203]
	v_pk_mul_f32 v[118:119], v[118:119], v[198:199]
	v_pk_mul_f32 v[114:115], v[114:115], v[194:195]
	v_pk_mul_f32 v[112:113], v[112:113], v[192:193]
	v_pk_mul_f32 v[108:109], v[108:109], v[204:205]
	v_pk_mul_f32 v[104:105], v[104:105], v[200:201]
	v_pk_mul_f32 v[100:101], v[100:101], v[196:197]
	v_pk_mul_f32 v[110:111], v[110:111], v[206:207]
	v_pk_mul_f32 v[106:107], v[106:107], v[202:203]
	v_pk_mul_f32 v[102:103], v[102:103], v[198:199]
	v_pk_mul_f32 v[98:99], v[98:99], v[194:195]
	v_pk_mul_f32 v[96:97], v[96:97], v[192:193]
	v_pk_mul_f32 v[92:93], v[92:93], v[204:205]
	v_pk_mul_f32 v[88:89], v[88:89], v[200:201]
	v_pk_mul_f32 v[84:85], v[84:85], v[196:197]
	v_pk_mul_f32 v[94:95], v[94:95], v[206:207]
	v_pk_mul_f32 v[90:91], v[90:91], v[202:203]
	v_pk_mul_f32 v[86:87], v[86:87], v[198:199]
	v_pk_mul_f32 v[82:83], v[82:83], v[194:195]
	v_pk_mul_f32 v[80:81], v[80:81], v[192:193]
	v_pk_mul_f32 v[76:77], v[76:77], v[204:205]
	v_pk_mul_f32 v[72:73], v[72:73], v[200:201]
	v_pk_mul_f32 v[68:69], v[68:69], v[196:197]
	v_pk_mul_f32 v[78:79], v[78:79], v[206:207]
	v_pk_mul_f32 v[74:75], v[74:75], v[202:203]
	v_pk_mul_f32 v[70:71], v[70:71], v[198:199]
	v_pk_mul_f32 v[66:67], v[66:67], v[194:195]
	v_pk_mul_f32 v[64:65], v[64:65], v[192:193]
	v_pk_mul_f32 v[60:61], v[60:61], v[204:205]
	v_pk_mul_f32 v[56:57], v[56:57], v[200:201]
	v_pk_mul_f32 v[52:53], v[52:53], v[196:197]
	v_pk_mul_f32 v[62:63], v[62:63], v[206:207]
	v_pk_mul_f32 v[58:59], v[58:59], v[202:203]
	v_pk_mul_f32 v[54:55], v[54:55], v[198:199]
	v_pk_mul_f32 v[50:51], v[50:51], v[194:195]
	v_pk_mul_f32 v[48:49], v[48:49], v[192:193]
	v_pk_mul_f32 v[44:45], v[44:45], v[204:205]
	v_pk_mul_f32 v[40:41], v[40:41], v[200:201]
	v_pk_mul_f32 v[36:37], v[36:37], v[196:197]
	v_pk_mul_f32 v[46:47], v[46:47], v[206:207]
	v_pk_mul_f32 v[42:43], v[42:43], v[202:203]
	v_pk_mul_f32 v[38:39], v[38:39], v[198:199]
	v_pk_mul_f32 v[34:35], v[34:35], v[194:195]
	v_pk_mul_f32 v[32:33], v[32:33], v[192:193]
	v_pk_mul_f32 v[28:29], v[28:29], v[204:205]
	v_pk_mul_f32 v[24:25], v[24:25], v[200:201]
	v_pk_mul_f32 v[20:21], v[20:21], v[196:197]
	v_pk_mul_f32 v[30:31], v[30:31], v[206:207]
	v_pk_mul_f32 v[26:27], v[26:27], v[202:203]
	v_pk_mul_f32 v[22:23], v[22:23], v[198:199]
	v_pk_mul_f32 v[18:19], v[18:19], v[194:195]
	v_pk_mul_f32 v[16:17], v[16:17], v[192:193]
.LBB0_517:
	v_cndmask_b32_e64 v231, v234, v231, s[4:5]
	v_mul_f32_e32 v192, 0xbe0293ee, v231
	v_fmamk_f32 v144, v144, 0x3e0293ee, v192
	v_fmamk_f32 v145, v145, 0x3e0293ee, v192
	v_fmamk_f32 v146, v146, 0x3e0293ee, v192
	v_fmamk_f32 v147, v147, 0x3e0293ee, v192
	v_fmamk_f32 v148, v148, 0x3e0293ee, v192
	v_fmamk_f32 v149, v149, 0x3e0293ee, v192
	v_fmamk_f32 v150, v150, 0x3e0293ee, v192
	v_fmamk_f32 v151, v151, 0x3e0293ee, v192
	s_cmp_gt_u32 s86, 61
	s_cbranch_scc1 .Ldq1_0
	s_add_u32 s96, s84, s22
	s_addc_u32 s97, s85, s23
	s_lshl_b32 s100, s74, 14
	s_add_i32 s100, s75, s100
	s_mov_b32 m0, s100
	v_lshl_add_u64 v[234:235], v[212:213], 1, s[96:97]
	global_load_lds_dwordx4 v[234:235], off
.Ldq1_0:
	v_fmamk_f32 v152, v152, 0x3e0293ee, v192
	v_fmamk_f32 v153, v153, 0x3e0293ee, v192
	v_fmamk_f32 v154, v154, 0x3e0293ee, v192
	v_fmamk_f32 v155, v155, 0x3e0293ee, v192
	v_fmamk_f32 v156, v156, 0x3e0293ee, v192
	v_fmamk_f32 v157, v157, 0x3e0293ee, v192
	v_fmamk_f32 v158, v158, 0x3e0293ee, v192
	v_fmamk_f32 v159, v159, 0x3e0293ee, v192
	s_cmp_gt_u32 s86, 61
	s_cbranch_scc1 .Ldq1_1
	s_add_i32 m0, s100, 0x400
	v_lshl_add_u64 v[234:235], v[214:215], 1, s[96:97]
	global_load_lds_dwordx4 v[234:235], off
.Ldq1_1:
	v_fmamk_f32 v128, v128, 0x3e0293ee, v192
	v_fmamk_f32 v129, v129, 0x3e0293ee, v192
	v_fmamk_f32 v130, v130, 0x3e0293ee, v192
	v_fmamk_f32 v131, v131, 0x3e0293ee, v192
	v_fmamk_f32 v132, v132, 0x3e0293ee, v192
	v_fmamk_f32 v133, v133, 0x3e0293ee, v192
	v_fmamk_f32 v134, v134, 0x3e0293ee, v192
	v_fmamk_f32 v135, v135, 0x3e0293ee, v192
	s_cmp_gt_u32 s86, 61
	s_cbranch_scc1 .Ldq1_2
	s_add_u32 s96, s68, s22
	s_addc_u32 s97, s69, s23
	s_add_u32 s96, s96, 0x26840000
	s_addc_u32 s97, s97, 0
	s_lshl_b32 s100, s74, 15
	s_add_i32 s100, s77, s100
	s_mov_b32 m0, s100
	v_lshl_add_u64 v[234:235], v[216:217], 1, s[96:97]
	global_load_lds_dwordx4 v[234:235], off
.Ldq1_2:
	v_fmamk_f32 v136, v136, 0x3e0293ee, v192
	v_fmamk_f32 v137, v137, 0x3e0293ee, v192
	v_fmamk_f32 v138, v138, 0x3e0293ee, v192
	v_fmamk_f32 v139, v139, 0x3e0293ee, v192
	v_fmamk_f32 v140, v140, 0x3e0293ee, v192
	v_fmamk_f32 v141, v141, 0x3e0293ee, v192
	v_fmamk_f32 v142, v142, 0x3e0293ee, v192
	v_fmac_f32_e32 v192, 0x3e0293ee, v143
	s_cmp_gt_u32 s86, 61
	s_cbranch_scc1 .Ldq1_3
	s_add_i32 m0, s100, 0x400
	v_lshl_add_u64 v[236:237], v[234:235], 0, s[8:9]
	global_load_lds_dwordx4 v[236:237], off
.Ldq1_3:
	v_exp_f32_e32 v143, v144
	v_exp_f32_e32 v145, v145
	v_exp_f32_e32 v146, v146
	v_exp_f32_e32 v147, v147
	v_exp_f32_e32 v148, v148
	v_exp_f32_e32 v193, v128
	v_exp_f32_e32 v149, v149
	v_add_f32_e32 v128, v145, v143
	v_exp_f32_e32 v150, v150
	s_cmp_gt_u32 s86, 61
	s_cbranch_scc1 .Ldq1_4
	s_add_i32 m0, s100, 0x800
	v_lshl_add_u64 v[236:237], v[234:235], 0, s[10:11]
	global_load_lds_dwordx4 v[236:237], off
.Ldq1_4:
	v_add_f32_e32 v128, v146, v128
	v_exp_f32_e32 v151, v151
	v_add_f32_e32 v128, v147, v128
	v_exp_f32_e32 v152, v152
	v_add_f32_e32 v128, v148, v128
	v_exp_f32_e32 v153, v153
	v_add_f32_e32 v128, v149, v128
	v_exp_f32_e32 v154, v154
	v_add_f32_e32 v128, v150, v128
	v_exp_f32_e32 v155, v155
	v_add_f32_e32 v128, v151, v128
	v_exp_f32_e32 v156, v156
	v_add_f32_e32 v128, v152, v128
	v_exp_f32_e32 v157, v157
	v_add_f32_e32 v128, v153, v128
	v_exp_f32_e32 v158, v158
	s_cmp_gt_u32 s86, 61
	s_cbranch_scc1 .Ldq1_5
	s_add_i32 m0, s100, 0xc00
	v_lshl_add_u64 v[234:235], v[234:235], 0, s[12:13]
	global_load_lds_dwordx4 v[234:235], off
.Ldq1_5:
	v_add_f32_e32 v128, v154, v128
	v_exp_f32_e32 v159, v159
	v_add_f32_e32 v128, v155, v128
	v_add_f32_e32 v128, v156, v128
	v_exp_f32_e32 v194, v129
	v_add_f32_e32 v128, v157, v128
	v_exp_f32_e32 v195, v130
	v_add_f32_e32 v128, v158, v128
	v_exp_f32_e32 v196, v131
	v_add_f32_e32 v128, v159, v128
	v_exp_f32_e32 v197, v132
	v_add_f32_e32 v128, v193, v128
	v_exp_f32_e32 v198, v133
	v_add_f32_e32 v128, v194, v128
	v_exp_f32_e32 v199, v134
	v_add_f32_e32 v128, v195, v128
	v_exp_f32_e32 v135, v135
	v_add_f32_e32 v128, v196, v128
	v_exp_f32_e32 v200, v136
	v_add_f32_e32 v128, v197, v128
	v_exp_f32_e32 v201, v137
	v_add_f32_e32 v128, v198, v128
	v_exp_f32_e32 v202, v138
	v_add_f32_e32 v128, v199, v128
	v_exp_f32_e32 v203, v139
	v_add_f32_e32 v128, v135, v128
	v_exp_f32_e32 v204, v140
	v_add_f32_e32 v128, v200, v128
	v_exp_f32_e32 v205, v141
	v_add_f32_e32 v128, v201, v128
	v_exp_f32_e32 v206, v142
	v_add_f32_e32 v128, v202, v128
	v_exp_f32_e32 v192, v192
	v_add_f32_e32 v128, v203, v128
	v_add_f32_e32 v128, v204, v128
	v_add_f32_e32 v128, v205, v128
	v_add_f32_e32 v128, v206, v128
	v_add_f32_e32 v128, v192, v128
	v_mov_b32_e32 v129, v128
	s_nop 1
	v_permlane32_swap_b32_e32 v128, v129
	v_add_f32_e32 v144, v128, v129
	v_fmac_f32_e32 v144, v232, v233
	v_cvt_pk_bf16_f32 v128, v143, v145
	v_cvt_pk_bf16_f32 v129, v146, v147
	v_cvt_pk_bf16_f32 v130, v148, v149
	v_cvt_pk_bf16_f32 v131, v150, v151
	v_cvt_pk_bf16_f32 v136, v152, v153
	v_cvt_pk_bf16_f32 v137, v154, v155
	v_cvt_pk_bf16_f32 v138, v156, v157
	v_cvt_pk_bf16_f32 v139, v158, v159
	v_cvt_pk_bf16_f32 v132, v193, v194
	v_cvt_pk_bf16_f32 v133, v195, v196
	v_cvt_pk_bf16_f32 v134, v197, v198
	v_cvt_pk_bf16_f32 v135, v199, v135
	v_cvt_pk_bf16_f32 v140, v200, v201
	v_cvt_pk_bf16_f32 v141, v202, v203
	v_cvt_pk_bf16_f32 v142, v204, v205
	v_cvt_pk_bf16_f32 v143, v206, v192
	v_lshl_add_u32 v145, s76, 15, v230
	ds_read_b64_tr_b16 v[146:147], v145 offset:0
	ds_read_b64_tr_b16 v[148:149], v145 offset:4096
	ds_read_b64_tr_b16 v[150:151], v145 offset:512
	ds_read_b64_tr_b16 v[152:153], v145 offset:4608
	ds_read_b64_tr_b16 v[154:155], v145 offset:1024
	ds_read_b64_tr_b16 v[156:157], v145 offset:5120
	ds_read_b64_tr_b16 v[192:193], v145 offset:1536
	ds_read_b64_tr_b16 v[194:195], v145 offset:5632
	ds_read_b64_tr_b16 v[196:197], v145 offset:2048
	ds_read_b64_tr_b16 v[198:199], v145 offset:6144
	ds_read_b64_tr_b16 v[200:201], v145 offset:2560
	ds_read_b64_tr_b16 v[202:203], v145 offset:6656
	ds_read_b64_tr_b16 v[204:205], v145 offset:3072
	ds_read_b64_tr_b16 v[206:207], v145 offset:7168
	s_waitcnt lgkmcnt(12)
	s_nop 0
	v_mfma_f32_32x32x16_bf16 v[0:15], v[128:131], v[146:149], v[0:15]
	ds_read_b64_tr_b16 v[232:233], v145 offset:3584
	ds_read_b64_tr_b16 v[234:235], v145 offset:7680
	s_waitcnt lgkmcnt(12)
	v_mfma_f32_32x32x16_bf16 v[112:127], v[128:131], v[150:153], v[112:127]
	ds_read_b64_tr_b16 v[146:147], v145 offset:8192
	ds_read_b64_tr_b16 v[148:149], v145 offset:12288
	s_waitcnt lgkmcnt(12)
	v_mfma_f32_32x32x16_bf16 v[96:111], v[128:131], v[154:157], v[96:111]
	ds_read_b64_tr_b16 v[150:151], v145 offset:8704
	ds_read_b64_tr_b16 v[152:153], v145 offset:12800
	s_waitcnt lgkmcnt(12)
	v_mfma_f32_32x32x16_bf16 v[80:95], v[128:131], v[192:195], v[80:95]
	ds_read_b64_tr_b16 v[154:155], v145 offset:9216
	ds_read_b64_tr_b16 v[156:157], v145 offset:13312
	s_waitcnt lgkmcnt(12)
	v_mfma_f32_32x32x16_bf16 v[64:79], v[128:131], v[196:199], v[64:79]
	ds_read_b64_tr_b16 v[192:193], v145 offset:9728
	ds_read_b64_tr_b16 v[194:195], v145 offset:13824
	s_waitcnt lgkmcnt(12)
	v_mfma_f32_32x32x16_bf16 v[48:63], v[128:131], v[200:203], v[48:63]
	ds_read_b64_tr_b16 v[196:197], v145 offset:10240
	ds_read_b64_tr_b16 v[198:199], v145 offset:14336
	s_waitcnt lgkmcnt(12)
	v_mfma_f32_32x32x16_bf16 v[32:47], v[128:131], v[204:207], v[32:47]
	ds_read_b64_tr_b16 v[200:201], v145 offset:10752
	ds_read_b64_tr_b16 v[202:203], v145 offset:14848
	s_waitcnt lgkmcnt(12)
	v_mfma_f32_32x32x16_bf16 v[16:31], v[128:131], v[232:235], v[16:31]
	ds_read_b64_tr_b16 v[204:205], v145 offset:11264
	ds_read_b64_tr_b16 v[206:207], v145 offset:15360
	s_waitcnt lgkmcnt(12)
	v_mfma_f32_32x32x16_bf16 v[0:15], v[136:139], v[146:149], v[0:15]
	ds_read_b64_tr_b16 v[232:233], v145 offset:11776
	ds_read_b64_tr_b16 v[234:235], v145 offset:15872
	s_waitcnt lgkmcnt(12)
	v_mfma_f32_32x32x16_bf16 v[112:127], v[136:139], v[150:153], v[112:127]
	ds_read_b64_tr_b16 v[146:147], v145 offset:16384
	ds_read_b64_tr_b16 v[148:149], v145 offset:20480
	s_waitcnt lgkmcnt(12)
	v_mfma_f32_32x32x16_bf16 v[96:111], v[136:139], v[154:157], v[96:111]
	ds_read_b64_tr_b16 v[150:151], v145 offset:16896
	ds_read_b64_tr_b16 v[152:153], v145 offset:20992
	s_waitcnt lgkmcnt(12)
	v_mfma_f32_32x32x16_bf16 v[80:95], v[136:139], v[192:195], v[80:95]
	ds_read_b64_tr_b16 v[154:155], v145 offset:17408
	ds_read_b64_tr_b16 v[156:157], v145 offset:21504
	s_waitcnt lgkmcnt(12)
	v_mfma_f32_32x32x16_bf16 v[64:79], v[136:139], v[196:199], v[64:79]
	ds_read_b64_tr_b16 v[192:193], v145 offset:17920
	ds_read_b64_tr_b16 v[194:195], v145 offset:22016
	s_waitcnt lgkmcnt(12)
	v_mfma_f32_32x32x16_bf16 v[48:63], v[136:139], v[200:203], v[48:63]
	ds_read_b64_tr_b16 v[196:197], v145 offset:18432
	ds_read_b64_tr_b16 v[198:199], v145 offset:22528
	s_waitcnt lgkmcnt(12)
	v_mfma_f32_32x32x16_bf16 v[32:47], v[136:139], v[204:207], v[32:47]
	ds_read_b64_tr_b16 v[200:201], v145 offset:18944
	ds_read_b64_tr_b16 v[202:203], v145 offset:23040
	s_waitcnt lgkmcnt(12)
	v_mfma_f32_32x32x16_bf16 v[16:31], v[136:139], v[232:235], v[16:31]
	ds_read_b64_tr_b16 v[204:205], v145 offset:19456
	ds_read_b64_tr_b16 v[206:207], v145 offset:23552
	s_waitcnt lgkmcnt(12)
	v_mfma_f32_32x32x16_bf16 v[0:15], v[132:135], v[146:149], v[0:15]
	ds_read_b64_tr_b16 v[232:233], v145 offset:19968
	ds_read_b64_tr_b16 v[234:235], v145 offset:24064
	s_waitcnt lgkmcnt(12)
	v_mfma_f32_32x32x16_bf16 v[112:127], v[132:135], v[150:153], v[112:127]
	ds_read_b64_tr_b16 v[146:147], v145 offset:24576
	ds_read_b64_tr_b16 v[148:149], v145 offset:28672
	s_waitcnt lgkmcnt(12)
	v_mfma_f32_32x32x16_bf16 v[96:111], v[132:135], v[154:157], v[96:111]
	ds_read_b64_tr_b16 v[150:151], v145 offset:25088
	ds_read_b64_tr_b16 v[152:153], v145 offset:29184
	s_waitcnt lgkmcnt(12)
	v_mfma_f32_32x32x16_bf16 v[80:95], v[132:135], v[192:195], v[80:95]
	ds_read_b64_tr_b16 v[154:155], v145 offset:25600
	ds_read_b64_tr_b16 v[156:157], v145 offset:29696
	s_waitcnt lgkmcnt(12)
	v_mfma_f32_32x32x16_bf16 v[64:79], v[132:135], v[196:199], v[64:79]
	ds_read_b64_tr_b16 v[192:193], v145 offset:26112
	ds_read_b64_tr_b16 v[194:195], v145 offset:30208
	s_waitcnt lgkmcnt(12)
	v_mfma_f32_32x32x16_bf16 v[48:63], v[132:135], v[200:203], v[48:63]
	ds_read_b64_tr_b16 v[196:197], v145 offset:26624
	ds_read_b64_tr_b16 v[198:199], v145 offset:30720
	s_waitcnt lgkmcnt(12)
	v_mfma_f32_32x32x16_bf16 v[32:47], v[132:135], v[204:207], v[32:47]
	ds_read_b64_tr_b16 v[200:201], v145 offset:27136
	ds_read_b64_tr_b16 v[202:203], v145 offset:31232
	s_waitcnt lgkmcnt(12)
	v_mfma_f32_32x32x16_bf16 v[16:31], v[132:135], v[232:235], v[16:31]
	ds_read_b64_tr_b16 v[204:205], v145 offset:27648
	ds_read_b64_tr_b16 v[206:207], v145 offset:31744
	s_waitcnt lgkmcnt(12)
	v_mfma_f32_32x32x16_bf16 v[0:15], v[140:143], v[146:149], v[0:15]
	ds_read_b64_tr_b16 v[232:233], v145 offset:28160
	ds_read_b64_tr_b16 v[234:235], v145 offset:32256
	s_waitcnt lgkmcnt(12)
	v_mfma_f32_32x32x16_bf16 v[112:127], v[140:143], v[150:153], v[112:127]
	s_waitcnt lgkmcnt(10)
	v_mfma_f32_32x32x16_bf16 v[96:111], v[140:143], v[154:157], v[96:111]
	s_waitcnt lgkmcnt(8)
	v_mfma_f32_32x32x16_bf16 v[80:95], v[140:143], v[192:195], v[80:95]
	s_waitcnt lgkmcnt(6)
	v_mfma_f32_32x32x16_bf16 v[64:79], v[140:143], v[196:199], v[64:79]
	s_add_i32 s4, s76, 1
	s_cmp_lg_u32 s76, 2
	s_cselect_b32 s76, s4, 0
	s_add_i32 s4, s74, 1
	s_cmp_lg_u32 s74, 2
	s_cselect_b32 s74, s4, 0
	s_add_u32 s22, s22, 0x20000
	s_waitcnt lgkmcnt(4)
	v_mfma_f32_32x32x16_bf16 v[48:63], v[140:143], v[200:203], v[48:63]
	s_addc_u32 s23, s23, 0
	s_add_i32 s86, s86, 1
	s_cmp_eq_u32 s22, 0x800000
	s_waitcnt lgkmcnt(2)
	v_mfma_f32_32x32x16_bf16 v[32:47], v[140:143], v[204:207], v[32:47]
	s_waitcnt lgkmcnt(0)
	v_mfma_f32_32x32x16_bf16 v[16:31], v[140:143], v[232:235], v[16:31]
	s_cbranch_scc1 .LBB0_521
	v_mov_b32_e32 v232, v144
	s_cmp_eq_u32 s22, 0x7e0000
	s_mov_b64 s[4:5], -1
	s_cbranch_scc1 .LBB0_510

.LBB0_904:
.LBB0_906:
	s_lshl_b32 s4, s80, 14
	v_add3_u32 v236, s4, v221, v220
	ds_read_b128 v[192:195], v236
	ds_read_b128 v[196:199], v236 offset:8192
	v_add3_u32 v236, s4, v222, v220
	ds_read_b128 v[200:203], v236
	ds_read_b128 v[204:207], v236 offset:8192
	v_add3_u32 v236, s4, v223, v220
	ds_read_b128 v[240:243], v236
	ds_read_b128 v[244:247], v236 offset:8192
	v_add3_u32 v236, s4, v225, v220
	ds_read_b128 v[248:251], v236
	ds_read_b128 v[252:255], v236 offset:8192
	s_waitcnt lgkmcnt(7)
	v_mfma_f32_32x32x16_bf16 v[144:159], v[192:195], v[160:163], 0
	s_waitcnt lgkmcnt(6)
	v_mfma_f32_32x32x16_bf16 v[128:143], v[196:199], v[160:163], 0
	v_add3_u32 v236, s4, v226, v220
	ds_read_b128 v[192:195], v236
	ds_read_b128 v[196:199], v236 offset:8192
	s_waitcnt lgkmcnt(7)
	v_mfma_f32_32x32x16_bf16 v[144:159], v[200:203], v[164:167], v[144:159]
	s_waitcnt lgkmcnt(6)
	v_mfma_f32_32x32x16_bf16 v[128:143], v[204:207], v[164:167], v[128:143]
	v_add3_u32 v236, s4, v227, v220
	ds_read_b128 v[200:203], v236
	ds_read_b128 v[204:207], v236 offset:8192
	s_waitcnt lgkmcnt(7)
	v_mfma_f32_32x32x16_bf16 v[144:159], v[240:243], v[168:171], v[144:159]
	s_waitcnt lgkmcnt(6)
	v_mfma_f32_32x32x16_bf16 v[128:143], v[244:247], v[168:171], v[128:143]
	v_add3_u32 v236, s4, v228, v220
	ds_read_b128 v[240:243], v236
	ds_read_b128 v[244:247], v236 offset:8192
	s_waitcnt lgkmcnt(7)
	v_mfma_f32_32x32x16_bf16 v[144:159], v[248:251], v[172:175], v[144:159]
	s_waitcnt lgkmcnt(6)
	v_mfma_f32_32x32x16_bf16 v[128:143], v[252:255], v[172:175], v[128:143]
	v_add3_u32 v236, s4, v229, v220
	ds_read_b128 v[248:251], v236
	ds_read_b128 v[252:255], v236 offset:8192
	s_waitcnt lgkmcnt(7)
	v_mfma_f32_32x32x16_bf16 v[144:159], v[192:195], v[176:179], v[144:159]
	s_waitcnt lgkmcnt(6)
	v_mfma_f32_32x32x16_bf16 v[128:143], v[196:199], v[176:179], v[128:143]
	s_waitcnt lgkmcnt(5)
	v_mfma_f32_32x32x16_bf16 v[144:159], v[200:203], v[180:183], v[144:159]
	s_waitcnt lgkmcnt(4)
	v_mfma_f32_32x32x16_bf16 v[128:143], v[204:207], v[180:183], v[128:143]
	s_waitcnt lgkmcnt(3)
	v_mfma_f32_32x32x16_bf16 v[144:159], v[240:243], v[184:187], v[144:159]
	s_waitcnt lgkmcnt(2)
	v_mfma_f32_32x32x16_bf16 v[128:143], v[244:247], v[184:187], v[128:143]
	s_waitcnt lgkmcnt(1)
	v_mfma_f32_32x32x16_bf16 v[144:159], v[248:251], v[188:191], v[144:159]
	s_waitcnt lgkmcnt(0)
	v_mfma_f32_32x32x16_bf16 v[128:143], v[252:255], v[188:191], v[128:143]
	v_max_f32_e32 v194, v231, v231
	s_nop 9
	v_max_f32_e32 v192, v144, v145
	v_max3_f32 v192, v192, v146, v147
	v_max3_f32 v192, v192, v148, v149
	v_max3_f32 v192, v192, v150, v151
	v_max3_f32 v192, v192, v152, v153
	v_max3_f32 v192, v192, v154, v155
	v_max3_f32 v192, v192, v156, v157
	v_max3_f32 v192, v192, v158, v159
	v_max3_f32 v192, v192, v128, v129
	v_max3_f32 v192, v192, v130, v131
	v_max3_f32 v192, v192, v132, v133
	v_max3_f32 v192, v192, v134, v135
	v_max3_f32 v192, v192, v136, v137
	v_max3_f32 v192, v192, v138, v139
	v_max3_f32 v192, v192, v140, v141
	v_max3_f32 v192, v192, v142, v143
	v_mov_b32_e32 v193, v192
	s_nop 1
	v_permlane32_swap_b32_e32 v192, v193
	v_max_f32_e32 v192, v192, v193
	v_max_f32_e32 v234, v194, v192
	v_sub_f32_e32 v193, v192, v231
	v_sub_f32_e32 v192, v231, v234
	v_mul_f32_e32 v192, 0x3e0293ee, v192
	v_exp_f32_e32 v192, v192
	v_cmp_ge_f32_e32 vcc, s42, v193
	s_cmp_eq_u64 vcc, exec
	s_cselect_b64 s[4:5], -1, 0
	v_cndmask_b32_e64 v233, v192, 1.0, s[4:5]
	v_cmp_gt_f32_e32 vcc, 1.0, v233
	s_cbranch_vccz .LBB0_910
	s_and_saveexec_b64 s[24:25], s[0:1]
	ds_write_b32 v224, v233 offset:128
	s_or_b64 exec, exec, s[24:25]
	s_waitcnt lgkmcnt(0)
	v_add_u32_e32 v192, s21, v210
	ds_read_b128 v[204:207], v192 offset:224
	ds_read_b128 v[200:203], v192 offset:192
	ds_read_b128 v[196:199], v192 offset:160
	ds_read_b128 v[192:195], v192 offset:128
	s_waitcnt lgkmcnt(3)
	v_pk_mul_f32 v[12:13], v[12:13], v[204:205]
	s_waitcnt lgkmcnt(2)
	v_pk_mul_f32 v[8:9], v[8:9], v[200:201]
	s_waitcnt lgkmcnt(1)
	v_pk_mul_f32 v[4:5], v[4:5], v[196:197]
	v_pk_mul_f32 v[14:15], v[14:15], v[206:207]
	v_pk_mul_f32 v[10:11], v[10:11], v[202:203]
	v_pk_mul_f32 v[6:7], v[6:7], v[198:199]
	s_waitcnt lgkmcnt(0)
	v_pk_mul_f32 v[2:3], v[2:3], v[194:195]
	v_pk_mul_f32 v[0:1], v[0:1], v[192:193]
	v_pk_mul_f32 v[124:125], v[124:125], v[204:205]
	v_pk_mul_f32 v[120:121], v[120:121], v[200:201]
	v_pk_mul_f32 v[116:117], v[116:117], v[196:197]
	v_pk_mul_f32 v[126:127], v[126:127], v[206:207]
	v_pk_mul_f32 v[122:123], v[122:123], v[202:203]
	v_pk_mul_f32 v[118:119], v[118:119], v[198:199]
	v_pk_mul_f32 v[114:115], v[114:115], v[194:195]
	v_pk_mul_f32 v[112:113], v[112:113], v[192:193]
	v_pk_mul_f32 v[108:109], v[108:109], v[204:205]
	v_pk_mul_f32 v[104:105], v[104:105], v[200:201]
	v_pk_mul_f32 v[100:101], v[100:101], v[196:197]
	v_pk_mul_f32 v[110:111], v[110:111], v[206:207]
	v_pk_mul_f32 v[106:107], v[106:107], v[202:203]
	v_pk_mul_f32 v[102:103], v[102:103], v[198:199]
	v_pk_mul_f32 v[98:99], v[98:99], v[194:195]
	v_pk_mul_f32 v[96:97], v[96:97], v[192:193]
	v_pk_mul_f32 v[92:93], v[92:93], v[204:205]
	v_pk_mul_f32 v[88:89], v[88:89], v[200:201]
	v_pk_mul_f32 v[84:85], v[84:85], v[196:197]
	v_pk_mul_f32 v[94:95], v[94:95], v[206:207]
	v_pk_mul_f32 v[90:91], v[90:91], v[202:203]
	v_pk_mul_f32 v[86:87], v[86:87], v[198:199]
	v_pk_mul_f32 v[82:83], v[82:83], v[194:195]
	v_pk_mul_f32 v[80:81], v[80:81], v[192:193]
	v_pk_mul_f32 v[76:77], v[76:77], v[204:205]
	v_pk_mul_f32 v[72:73], v[72:73], v[200:201]
	v_pk_mul_f32 v[68:69], v[68:69], v[196:197]
	v_pk_mul_f32 v[78:79], v[78:79], v[206:207]
	v_pk_mul_f32 v[74:75], v[74:75], v[202:203]
	v_pk_mul_f32 v[70:71], v[70:71], v[198:199]
	v_pk_mul_f32 v[66:67], v[66:67], v[194:195]
	v_pk_mul_f32 v[64:65], v[64:65], v[192:193]
	v_pk_mul_f32 v[60:61], v[60:61], v[204:205]
	v_pk_mul_f32 v[56:57], v[56:57], v[200:201]
	v_pk_mul_f32 v[52:53], v[52:53], v[196:197]
	v_pk_mul_f32 v[62:63], v[62:63], v[206:207]
	v_pk_mul_f32 v[58:59], v[58:59], v[202:203]
	v_pk_mul_f32 v[54:55], v[54:55], v[198:199]
	v_pk_mul_f32 v[50:51], v[50:51], v[194:195]
	v_pk_mul_f32 v[48:49], v[48:49], v[192:193]
	v_pk_mul_f32 v[44:45], v[44:45], v[204:205]
	v_pk_mul_f32 v[40:41], v[40:41], v[200:201]
	v_pk_mul_f32 v[36:37], v[36:37], v[196:197]
	v_pk_mul_f32 v[46:47], v[46:47], v[206:207]
	v_pk_mul_f32 v[42:43], v[42:43], v[202:203]
	v_pk_mul_f32 v[38:39], v[38:39], v[198:199]
	v_pk_mul_f32 v[34:35], v[34:35], v[194:195]
	v_pk_mul_f32 v[32:33], v[32:33], v[192:193]
	v_pk_mul_f32 v[28:29], v[28:29], v[204:205]
	v_pk_mul_f32 v[24:25], v[24:25], v[200:201]
	v_pk_mul_f32 v[20:21], v[20:21], v[196:197]
	v_pk_mul_f32 v[30:31], v[30:31], v[206:207]
	v_pk_mul_f32 v[26:27], v[26:27], v[202:203]
	v_pk_mul_f32 v[22:23], v[22:23], v[198:199]
	v_pk_mul_f32 v[18:19], v[18:19], v[194:195]
	v_pk_mul_f32 v[16:17], v[16:17], v[192:193]
.LBB0_910:
	v_cndmask_b32_e64 v231, v234, v231, s[4:5]
	v_mul_f32_e32 v192, 0xbe0293ee, v231
	v_fmamk_f32 v144, v144, 0x3e0293ee, v192
	v_fmamk_f32 v145, v145, 0x3e0293ee, v192
	v_fmamk_f32 v146, v146, 0x3e0293ee, v192
	v_fmamk_f32 v147, v147, 0x3e0293ee, v192
	v_fmamk_f32 v148, v148, 0x3e0293ee, v192
	v_fmamk_f32 v149, v149, 0x3e0293ee, v192
	v_fmamk_f32 v150, v150, 0x3e0293ee, v192
	v_fmamk_f32 v151, v151, 0x3e0293ee, v192
	s_cmp_gt_u32 s86, 61
	s_cbranch_scc1 .Ldq0_0
	s_add_u32 s96, s84, s22
	s_addc_u32 s97, s85, s23
	s_lshl_b32 s100, s78, 14
	s_add_i32 s100, s79, s100
	s_mov_b32 m0, s100
	v_lshl_add_u64 v[234:235], v[212:213], 1, s[96:97]
	global_load_lds_dwordx4 v[234:235], off

.Ldq0_1:
	v_fmamk_f32 v128, v128, 0x3e0293ee, v192
	v_fmamk_f32 v129, v129, 0x3e0293ee, v192
	v_fmamk_f32 v130, v130, 0x3e0293ee, v192
	v_fmamk_f32 v131, v131, 0x3e0293ee, v192
	v_fmamk_f32 v132, v132, 0x3e0293ee, v192
	v_fmamk_f32 v133, v133, 0x3e0293ee, v192
	v_fmamk_f32 v134, v134, 0x3e0293ee, v192
	v_fmamk_f32 v135, v135, 0x3e0293ee, v192
	s_cmp_gt_u32 s86, 61
	s_cbranch_scc1 .Ldq0_2
	s_add_u32 s96, s76, s22
	s_addc_u32 s97, s77, s23
	s_add_u32 s96, s96, 0x26840000
	s_addc_u32 s97, s97, 0
	s_lshl_b32 s100, s78, 15
	s_add_i32 s100, s81, s100
	s_mov_b32 m0, s100
	v_lshl_add_u64 v[234:235], v[216:217], 1, s[96:97]
	global_load_lds_dwordx4 v[234:235], off

.Ldq0_5:
	v_add_f32_e32 v128, v154, v128
	v_exp_f32_e32 v159, v159
	v_add_f32_e32 v128, v155, v128
	v_add_f32_e32 v128, v156, v128
	v_exp_f32_e32 v194, v129
	v_add_f32_e32 v128, v157, v128
	v_exp_f32_e32 v195, v130
	v_add_f32_e32 v128, v158, v128
	v_exp_f32_e32 v196, v131
	v_add_f32_e32 v128, v159, v128
	v_exp_f32_e32 v197, v132
	v_add_f32_e32 v128, v193, v128
	v_exp_f32_e32 v198, v133
	v_add_f32_e32 v128, v194, v128
	v_exp_f32_e32 v199, v134
	v_add_f32_e32 v128, v195, v128
	v_exp_f32_e32 v135, v135
	v_add_f32_e32 v128, v196, v128
	v_exp_f32_e32 v200, v136
	v_add_f32_e32 v128, v197, v128
	v_exp_f32_e32 v201, v137
	v_add_f32_e32 v128, v198, v128
	v_exp_f32_e32 v202, v138
	v_add_f32_e32 v128, v199, v128
	v_exp_f32_e32 v203, v139
	v_add_f32_e32 v128, v135, v128
	v_exp_f32_e32 v204, v140
	v_add_f32_e32 v128, v200, v128
	v_exp_f32_e32 v205, v141
	v_add_f32_e32 v128, v201, v128
	v_exp_f32_e32 v206, v142
	v_add_f32_e32 v128, v202, v128
	v_exp_f32_e32 v192, v192
	v_add_f32_e32 v128, v203, v128
	v_add_f32_e32 v128, v204, v128
	v_add_f32_e32 v128, v205, v128
	v_add_f32_e32 v128, v206, v128
	v_add_f32_e32 v128, v192, v128
	v_mov_b32_e32 v129, v128
	s_nop 1
	v_permlane32_swap_b32_e32 v128, v129
	v_add_f32_e32 v144, v128, v129
	v_fmac_f32_e32 v144, v232, v233
	v_cvt_pk_bf16_f32 v128, v143, v145
	v_cvt_pk_bf16_f32 v129, v146, v147
	v_cvt_pk_bf16_f32 v130, v148, v149
	v_cvt_pk_bf16_f32 v131, v150, v151
	v_cvt_pk_bf16_f32 v136, v152, v153
	v_cvt_pk_bf16_f32 v137, v154, v155
	v_cvt_pk_bf16_f32 v138, v156, v157
	v_cvt_pk_bf16_f32 v139, v158, v159
	v_cvt_pk_bf16_f32 v132, v193, v194
	v_cvt_pk_bf16_f32 v133, v195, v196
	v_cvt_pk_bf16_f32 v134, v197, v198
	v_cvt_pk_bf16_f32 v135, v199, v135
	v_cvt_pk_bf16_f32 v140, v200, v201
	v_cvt_pk_bf16_f32 v141, v202, v203
	v_cvt_pk_bf16_f32 v142, v204, v205
	v_cvt_pk_bf16_f32 v143, v206, v192
	v_lshl_add_u32 v145, s80, 15, v230
	ds_read_b64_tr_b16 v[146:147], v145 offset:0
	ds_read_b64_tr_b16 v[148:149], v145 offset:4096
	ds_read_b64_tr_b16 v[150:151], v145 offset:512
	ds_read_b64_tr_b16 v[152:153], v145 offset:4608
	ds_read_b64_tr_b16 v[154:155], v145 offset:1024
	ds_read_b64_tr_b16 v[156:157], v145 offset:5120
	ds_read_b64_tr_b16 v[192:193], v145 offset:1536
	ds_read_b64_tr_b16 v[194:195], v145 offset:5632
	ds_read_b64_tr_b16 v[196:197], v145 offset:2048
	ds_read_b64_tr_b16 v[198:199], v145 offset:6144
	ds_read_b64_tr_b16 v[200:201], v145 offset:2560
	ds_read_b64_tr_b16 v[202:203], v145 offset:6656
	ds_read_b64_tr_b16 v[204:205], v145 offset:3072
	ds_read_b64_tr_b16 v[206:207], v145 offset:7168
	s_waitcnt lgkmcnt(12)
	s_nop 0
	v_mfma_f32_32x32x16_bf16 v[0:15], v[128:131], v[146:149], v[0:15]
	ds_read_b64_tr_b16 v[232:233], v145 offset:3584
	ds_read_b64_tr_b16 v[234:235], v145 offset:7680
	s_waitcnt lgkmcnt(12)
	v_mfma_f32_32x32x16_bf16 v[112:127], v[128:131], v[150:153], v[112:127]
	ds_read_b64_tr_b16 v[146:147], v145 offset:8192
	ds_read_b64_tr_b16 v[148:149], v145 offset:12288
	s_waitcnt lgkmcnt(12)
	v_mfma_f32_32x32x16_bf16 v[96:111], v[128:131], v[154:157], v[96:111]
	ds_read_b64_tr_b16 v[150:151], v145 offset:8704
	ds_read_b64_tr_b16 v[152:153], v145 offset:12800
	s_waitcnt lgkmcnt(12)
	v_mfma_f32_32x32x16_bf16 v[80:95], v[128:131], v[192:195], v[80:95]
	ds_read_b64_tr_b16 v[154:155], v145 offset:9216
	ds_read_b64_tr_b16 v[156:157], v145 offset:13312
	s_waitcnt lgkmcnt(12)
	v_mfma_f32_32x32x16_bf16 v[64:79], v[128:131], v[196:199], v[64:79]
	ds_read_b64_tr_b16 v[192:193], v145 offset:9728
	ds_read_b64_tr_b16 v[194:195], v145 offset:13824
	s_waitcnt lgkmcnt(12)
	v_mfma_f32_32x32x16_bf16 v[48:63], v[128:131], v[200:203], v[48:63]
	ds_read_b64_tr_b16 v[196:197], v145 offset:10240
	ds_read_b64_tr_b16 v[198:199], v145 offset:14336
	s_waitcnt lgkmcnt(12)
	v_mfma_f32_32x32x16_bf16 v[32:47], v[128:131], v[204:207], v[32:47]
	ds_read_b64_tr_b16 v[200:201], v145 offset:10752
	ds_read_b64_tr_b16 v[202:203], v145 offset:14848
	s_waitcnt lgkmcnt(12)
	v_mfma_f32_32x32x16_bf16 v[16:31], v[128:131], v[232:235], v[16:31]
	ds_read_b64_tr_b16 v[204:205], v145 offset:11264
	ds_read_b64_tr_b16 v[206:207], v145 offset:15360
	s_waitcnt lgkmcnt(12)
	v_mfma_f32_32x32x16_bf16 v[0:15], v[136:139], v[146:149], v[0:15]
	ds_read_b64_tr_b16 v[232:233], v145 offset:11776
	ds_read_b64_tr_b16 v[234:235], v145 offset:15872
	s_waitcnt lgkmcnt(12)
	v_mfma_f32_32x32x16_bf16 v[112:127], v[136:139], v[150:153], v[112:127]
	ds_read_b64_tr_b16 v[146:147], v145 offset:16384
	ds_read_b64_tr_b16 v[148:149], v145 offset:20480
	s_waitcnt lgkmcnt(12)
	v_mfma_f32_32x32x16_bf16 v[96:111], v[136:139], v[154:157], v[96:111]
	ds_read_b64_tr_b16 v[150:151], v145 offset:16896
	ds_read_b64_tr_b16 v[152:153], v145 offset:20992
	s_waitcnt lgkmcnt(12)
	v_mfma_f32_32x32x16_bf16 v[80:95], v[136:139], v[192:195], v[80:95]
	ds_read_b64_tr_b16 v[154:155], v145 offset:17408
	ds_read_b64_tr_b16 v[156:157], v145 offset:21504
	s_waitcnt lgkmcnt(12)
	v_mfma_f32_32x32x16_bf16 v[64:79], v[136:139], v[196:199], v[64:79]
	ds_read_b64_tr_b16 v[192:193], v145 offset:17920
	ds_read_b64_tr_b16 v[194:195], v145 offset:22016
	s_waitcnt lgkmcnt(12)
	v_mfma_f32_32x32x16_bf16 v[48:63], v[136:139], v[200:203], v[48:63]
	ds_read_b64_tr_b16 v[196:197], v145 offset:18432
	ds_read_b64_tr_b16 v[198:199], v145 offset:22528
	s_waitcnt lgkmcnt(12)
	v_mfma_f32_32x32x16_bf16 v[32:47], v[136:139], v[204:207], v[32:47]
	ds_read_b64_tr_b16 v[200:201], v145 offset:18944
	ds_read_b64_tr_b16 v[202:203], v145 offset:23040
	s_waitcnt lgkmcnt(12)
	v_mfma_f32_32x32x16_bf16 v[16:31], v[136:139], v[232:235], v[16:31]
	ds_read_b64_tr_b16 v[204:205], v145 offset:19456
	ds_read_b64_tr_b16 v[206:207], v145 offset:23552
	s_waitcnt lgkmcnt(12)
	v_mfma_f32_32x32x16_bf16 v[0:15], v[132:135], v[146:149], v[0:15]
	ds_read_b64_tr_b16 v[232:233], v145 offset:19968
	ds_read_b64_tr_b16 v[234:235], v145 offset:24064
	s_waitcnt lgkmcnt(12)
	v_mfma_f32_32x32x16_bf16 v[112:127], v[132:135], v[150:153], v[112:127]
	ds_read_b64_tr_b16 v[146:147], v145 offset:24576
	ds_read_b64_tr_b16 v[148:149], v145 offset:28672
	s_waitcnt lgkmcnt(12)
	v_mfma_f32_32x32x16_bf16 v[96:111], v[132:135], v[154:157], v[96:111]
	ds_read_b64_tr_b16 v[150:151], v145 offset:25088
	ds_read_b64_tr_b16 v[152:153], v145 offset:29184
	s_waitcnt lgkmcnt(12)
	v_mfma_f32_32x32x16_bf16 v[80:95], v[132:135], v[192:195], v[80:95]
	ds_read_b64_tr_b16 v[154:155], v145 offset:25600
	ds_read_b64_tr_b16 v[156:157], v145 offset:29696
	s_waitcnt lgkmcnt(12)
	v_mfma_f32_32x32x16_bf16 v[64:79], v[132:135], v[196:199], v[64:79]
	ds_read_b64_tr_b16 v[192:193], v145 offset:26112
	ds_read_b64_tr_b16 v[194:195], v145 offset:30208
	s_waitcnt lgkmcnt(12)
	v_mfma_f32_32x32x16_bf16 v[48:63], v[132:135], v[200:203], v[48:63]
	ds_read_b64_tr_b16 v[196:197], v145 offset:26624
	ds_read_b64_tr_b16 v[198:199], v145 offset:30720
	s_waitcnt lgkmcnt(12)
	v_mfma_f32_32x32x16_bf16 v[32:47], v[132:135], v[204:207], v[32:47]
	ds_read_b64_tr_b16 v[200:201], v145 offset:27136
	ds_read_b64_tr_b16 v[202:203], v145 offset:31232
	s_waitcnt lgkmcnt(12)
	v_mfma_f32_32x32x16_bf16 v[16:31], v[132:135], v[232:235], v[16:31]
	ds_read_b64_tr_b16 v[204:205], v145 offset:27648
	ds_read_b64_tr_b16 v[206:207], v145 offset:31744
	s_waitcnt lgkmcnt(12)
	v_mfma_f32_32x32x16_bf16 v[0:15], v[140:143], v[146:149], v[0:15]
	ds_read_b64_tr_b16 v[232:233], v145 offset:28160
	ds_read_b64_tr_b16 v[234:235], v145 offset:32256
	s_waitcnt lgkmcnt(12)
	v_mfma_f32_32x32x16_bf16 v[112:127], v[140:143], v[150:153], v[112:127]
	s_waitcnt lgkmcnt(10)
	v_mfma_f32_32x32x16_bf16 v[96:111], v[140:143], v[154:157], v[96:111]
	s_waitcnt lgkmcnt(8)
	v_mfma_f32_32x32x16_bf16 v[80:95], v[140:143], v[192:195], v[80:95]
	s_waitcnt lgkmcnt(6)
	v_mfma_f32_32x32x16_bf16 v[64:79], v[140:143], v[196:199], v[64:79]
	s_add_i32 s4, s80, 1
	s_cmp_lg_u32 s80, 2
	s_cselect_b32 s80, s4, 0
	s_add_i32 s4, s78, 1
	s_cmp_lg_u32 s78, 2
	s_cselect_b32 s78, s4, 0
	s_add_u32 s22, s22, 0x20000
	s_waitcnt lgkmcnt(4)
	v_mfma_f32_32x32x16_bf16 v[48:63], v[140:143], v[200:203], v[48:63]
	s_addc_u32 s23, s23, 0
	s_add_i32 s86, s86, 1
	s_cmp_eq_u32 s22, 0x800000
	s_waitcnt lgkmcnt(2)
	v_mfma_f32_32x32x16_bf16 v[32:47], v[140:143], v[204:207], v[32:47]
	s_waitcnt lgkmcnt(0)
	v_mfma_f32_32x32x16_bf16 v[16:31], v[140:143], v[232:235], v[16:31]
	s_cbranch_scc1 .LBB0_914
	v_mov_b32_e32 v232, v144
	s_cmp_eq_u32 s22, 0x7e0000
	s_mov_b64 s[4:5], -1
	s_cbranch_scc1 .LBB0_903
